# E47: E41 + mem-attention prompt epilogue store widening (E28) + prompt-FoX row-max tree without self-max canonicalisation (8 fewer VALU per tile)
# baseline (speedup 1.0000x reference)
.LBB0_1393:
	v_max_f32_e32 v4, v50, v51
	v_max3_f32 v2, v82, v83, v84
	v_max3_f32 v4, v4, v52, v53
	v_max3_f32 v2, v2, v85, v86
	v_max3_f32 v4, v4, v54, v55
	v_max3_f32 v2, v2, v87, v88
	v_max3_f32 v4, v4, v56, v57
	v_max3_f32 v2, v2, v89, v90
	v_max3_f32 v4, v4, v58, v59
	v_max3_f32 v2, v2, v91, v92
	v_max3_f32 v4, v4, v60, v61
	v_max3_f32 v2, v2, v93, v94
	v_max3_f32 v4, v4, v62, v63
	v_max3_f32 v2, v2, v95, v96
	v_max3_f32 v4, v4, v64, v65
	v_max3_f32 v2, v2, v97, v4
	v_max_f32_e32 v4, v66, v67
	v_max_f32_e32 v5, v98, v99
	v_max3_f32 v4, v4, v68, v69
	v_max3_f32 v5, v5, v100, v101
	v_max3_f32 v4, v4, v70, v71
	v_max3_f32 v5, v5, v102, v103
	v_max3_f32 v4, v4, v72, v73
	v_max3_f32 v5, v5, v104, v105
	v_max3_f32 v4, v4, v74, v75
	v_max3_f32 v5, v5, v106, v107
	v_max3_f32 v4, v4, v76, v77
	v_max3_f32 v5, v5, v108, v109
	v_max3_f32 v4, v4, v78, v79
	v_max3_f32 v5, v5, v110, v111
	v_max3_f32 v4, v4, v80, v81
	v_max3_f32 v5, v5, v112, v113
	v_max3_f32 v2, v2, v4, v5
	v_mov_b32_e32 v4, v2
	s_nop 1
	v_permlane32_swap_b32_e32 v2, v4
	v_max_f32_e32 v2, v2, v4
	v_add_f32_e32 v4, 0x41a00000, v158
	v_cmp_gt_f32_e32 vcc, v2, v4
	s_cbranch_vccz .LBB0_1395
	v_max_f32_e32 v2, v2, v2
	v_max_f32_e32 v4, v158, v158
	v_max_f32_e32 v4, v4, v2
	v_sub_f32_e32 v2, v158, v4
	v_exp_f32_e32 v2, v2
	v_mov_b32_e32 v158, v4
	v_pk_mul_f32 v[48:49], v[48:49], v[2:3] op_sel_hi:[1,0]
	v_pk_mul_f32 v[46:47], v[46:47], v[2:3] op_sel_hi:[1,0]
	v_pk_mul_f32 v[44:45], v[44:45], v[2:3] op_sel_hi:[1,0]
	v_pk_mul_f32 v[42:43], v[42:43], v[2:3] op_sel_hi:[1,0]
	v_pk_mul_f32 v[40:41], v[40:41], v[2:3] op_sel_hi:[1,0]
	v_pk_mul_f32 v[38:39], v[38:39], v[2:3] op_sel_hi:[1,0]
	v_pk_mul_f32 v[36:37], v[36:37], v[2:3] op_sel_hi:[1,0]
	v_pk_mul_f32 v[34:35], v[34:35], v[2:3] op_sel_hi:[1,0]
	v_pk_mul_f32 v[32:33], v[32:33], v[2:3] op_sel_hi:[1,0]
	v_pk_mul_f32 v[30:31], v[30:31], v[2:3] op_sel_hi:[1,0]
	v_pk_mul_f32 v[28:29], v[28:29], v[2:3] op_sel_hi:[1,0]
	v_pk_mul_f32 v[26:27], v[26:27], v[2:3] op_sel_hi:[1,0]
	v_pk_mul_f32 v[24:25], v[24:25], v[2:3] op_sel_hi:[1,0]
	v_pk_mul_f32 v[22:23], v[22:23], v[2:3] op_sel_hi:[1,0]
	v_pk_mul_f32 v[20:21], v[20:21], v[2:3] op_sel_hi:[1,0]
	v_pk_mul_f32 v[18:19], v[18:19], v[2:3] op_sel_hi:[1,0]
	v_mul_f32_e32 v192, v192, v2
